# early L1 invalidate in grid barriers + xq GEMM and cross-attention fused per workgroup (units remapped to the tile the workgroup just wrote; grid barrier between them replaced by a workgroup barrier)
# baseline (speedup 1.0000x reference)
; DI bf16_t f2bf(float f) { return (bf16_t)(pk2(f, 0.f) & 0xffffu); }
; DI int crow(int r, int hi) { return (r & 3) + 8 * (r >> 2) + 4 * hi; }
; #define PP (kp_get())
; template <bool DIFF>
; DI void attn2_unit(int qb, const bf16_t* QO  , bf16_t* Ob, const bf16_t* K, const bf16_t* V  ,
;                    int ntile, float lam, const float* gain, float post, LAS unsigned char* lds) {
;     ...
;     float a1[16], a2[16];
;     { const float l1 = half_swap_sum(ls[0]); bcast_rows(wsf, 1.f / l1, r32, hi, a1); }
;     if (DIFF) { const float l2 = half_swap_sum(ls[1]); bcast_rows(wsf, -lam / l2, r32, hi, a2); }
; #pragma unroll
;     for (int d = 0; d < 4; ++d)
; #pragma unroll
;         for (int i = 0; i < 16; ++i) { o1[d][i] *= a1[i]; if (DIFF) o1[d][i] += o2[d][i] * a2[i]; }
;     bf16_t* ob = Ob + (size_t)q0w * 512 + r32;
;     if (DIFF) {
;         const float g0 = gain[r32] * post, g1 = gain[32 + r32] * post, g2 = gain[64 + r32] * post, g3 = gain[96 + r32] * post;
; #pragma unroll
;         for (int i = 0; i < 16; ++i) {
;             float ss = o1[0][i] * o1[0][i] + o1[1][i] * o1[1][i] + o1[2][i] * o1[2][i] + o1[3][i] * o1[3][i];
;             ss += __shfl_xor(ss, 1); ss += __shfl_xor(ss, 2); ss += __shfl_xor(ss, 4); ss += __shfl_xor(ss, 8); ss += __shfl_xor(ss, 16);
;             const float rs = rsqrtf(ss * (1.f / 128.f) + RMS_EPS);
;             bf16_t* rp = ob + (size_t)crow(i, hi) * 512;
;             rp[0] = f2bf(o1[0][i] * rs * g0); rp[32] = f2bf(o1[1][i] * rs * g1); rp[64] = f2bf(o1[2][i] * rs * g2); rp[96] = f2bf(o1[3][i] * rs * g3);
;         }
;     } else {
; #pragma unroll
;         for (int i = 0; i < 16; ++i) { bf16_t* rp = ob + (size_t)crow(i, hi) * 512;
;             rp[0] = f2bf(o1[0][i]); rp[32] = f2bf(o1[1][i]); rp[64] = f2bf(o1[2][i]); rp[96] = f2bf(o1[3][i]); }
; __global__ void __launch_bounds__(512, 2) fwd_megakernel(Params P) {
;     ...
;         xcd_barrier(xbar);
;         for (int idx = c; idx < 512; idx += G) { const int qb = idx & 15, bh = idx >> 4, b = bh >> 2, hh = bh & 3;
;             const bf16_t* kb = (const bf16_t*)(PP->ws + WS_MEMKV) + (size_t)(l * 2) * 2048 * 512 + (size_t)b * MEML * 512 + hh * 128;
;             attn2_unit<false>(qb, (const bf16_t*)(PP->ws + WS_XQ) + (size_t)b * SEQ * 512 + hh * 128, (bf16_t*)(PP->ws + WS_XQ) + (size_t)b * SEQ * 512 + hh * 128, kb, kb + (size_t)2048 * 512, 4, 0.f, nullptr, 1.f, lds); }
.LBB0_1074:
	s_waitcnt vmcnt(0)
	v_mov_b32_e32 v0, v196
	s_waitcnt vmcnt(0) lgkmcnt(0)
	s_barrier
	s_nop 0
	v_cmp_eq_u32_e32 vcc, 0, v0
	buffer_inv sc1
	s_waitcnt vmcnt(0)
	s_mov_b64 s[30:31], exec
	s_branch .LBB0_1126
.LBB0_1126:
	s_or_b64 exec, exec, s[30:31]
	v_readlane_b32 s12, v252, 28
	v_readlane_b32 s13, v252, 29
	s_and_b64 vcc, exec, s[12:13]
	s_mov_b64 s[50:51], 0x9a00000
	s_waitcnt lgkmcnt(0)
	s_barrier
	s_cbranch_vccnz .LBB0_1186
	s_lshl_b32 s12, s48, 21
	s_lshl_b32 s12, s12, 1
	s_and_b32 s14, s2, 7
	s_lshl_b32 s14, s14, 5
	s_lshr_b32 s15, s2, 3
	s_add_i32 s14, s14, s15
	s_lshr_b32 s15, s14, 4
	s_lshl_b32 s15, s15, 3
	s_and_b32 s16, s14, 7
	s_add_i32 s15, s15, s16
	s_bfe_u32 s16, s14, 0x10003
	s_lshr_b32 s17, s15, 4
	s_and_b32 s15, s15, 15
	s_lshl_b32 s17, s17, 6
	s_lshl_b32 s16, s16, 5
	s_add_i32 s14, s15, s17
	s_add_i32 s14, s14, s16
	s_lshl_b32 s13, s14, 3
	s_branch .LBB0_1129
.LBB0_1128:
	s_or_b64 exec, exec, s[30:31]
	s_lshl_b64 s[30:31], s[62:63], 1
	s_add_u32 s17, s64, s30
	s_addc_u32 s25, s65, s31
	s_lshl_b32 s15, s15, 1
	s_add_u32 s15, s17, s15
	s_addc_u32 s25, s25, 0
	s_ashr_i32 s49, s48, 31
	s_waitcnt lgkmcnt(0)
	v_add_u32_e32 v0, s16, v0
	s_lshl_b64 s[16:17], s[48:49], 10
	ds_read_b128 v[66:69], v0
	ds_read_b128 v[70:73], v0 offset:32
	ds_read_b128 v[74:77], v0 offset:64
	ds_read_b128 v[78:81], v0 offset:96
	s_add_u32 s16, s15, s16
	s_addc_u32 s17, s25, s17
	v_lshlrev_b32_e32 v0, 1, v136
	s_waitcnt lgkmcnt(3)
	v_mul_f32_e32 v34, v34, v66
	v_mul_f32_e32 v35, v35, v67
	v_mul_f32_e32 v50, v50, v66
	v_mul_f32_e32 v51, v51, v67
	v_mul_f32_e32 v18, v18, v66
	v_mul_f32_e32 v19, v19, v67
	v_mul_f32_e32 v66, v2, v66
	v_mul_f32_e32 v67, v3, v67
	v_lshl_add_u64 v[2:3], s[16:17], 0, v[0:1]
	v_lshlrev_b32_e32 v0, 12, v131
	v_lshl_add_u64 v[2:3], v[2:3], 0, v[0:1]
	s_waitcnt lgkmcnt(2)
	v_mul_f32_e32 v38, v38, v70
	v_mul_f32_e32 v54, v54, v70
	v_mul_f32_e32 v22, v22, v70
	v_mul_f32_e32 v70, v6, v70
	v_add_co_u32_e32 v6, vcc, s66, v2
	v_mul_f32_e32 v39, v39, v71
	v_mul_f32_e32 v55, v55, v71
	v_mul_f32_e32 v23, v23, v71
	v_mul_f32_e32 v71, v7, v71
	s_mov_b64 s[50:51], 0x9a00000
	v_cvt_pk_bf16_f32 v0, v34, s0
	v_addc_co_u32_e32 v7, vcc, 0, v3, vcc
	s_waitcnt lgkmcnt(0)
	v_mul_f32_e32 v36, v36, v68
	v_mul_f32_e32 v37, v37, v69
	v_mul_f32_e32 v52, v52, v68
	v_mul_f32_e32 v53, v53, v69
	v_mul_f32_e32 v20, v20, v68
	v_mul_f32_e32 v21, v21, v69
	v_mul_f32_e32 v68, v4, v68
	v_mul_f32_e32 v69, v5, v69
	v_lshl_add_u64 v[4:5], v[2:3], 0, s[50:51]
	global_store_short v[6:7], v0, off
	v_cvt_pk_bf16_f32 v0, v50, s0
	global_store_short v[4:5], v0, off offset:64
	v_cvt_pk_bf16_f32 v0, v18, s0
	global_store_short v[4:5], v0, off offset:128
	v_cvt_pk_bf16_f32 v0, v66, s0
	global_store_short v[4:5], v0, off offset:192
	v_cvt_pk_bf16_f32 v0, v35, s0
	global_store_short v[4:5], v0, off offset:1024
	v_cvt_pk_bf16_f32 v0, v51, s0
	global_store_short v[4:5], v0, off offset:1088
	v_cvt_pk_bf16_f32 v0, v19, s0
	global_store_short v[4:5], v0, off offset:1152
	v_cvt_pk_bf16_f32 v0, v67, s0
	global_store_short v[4:5], v0, off offset:1216
	v_cvt_pk_bf16_f32 v0, v36, s0
	global_store_short v[4:5], v0, off offset:2048
	v_cvt_pk_bf16_f32 v0, v52, s0
	global_store_short v[4:5], v0, off offset:2112
	v_cvt_pk_bf16_f32 v0, v20, s0
	global_store_short v[4:5], v0, off offset:2176
	v_cvt_pk_bf16_f32 v0, v68, s0
	global_store_short v[4:5], v0, off offset:2240
	v_cvt_pk_bf16_f32 v0, v37, s0
	global_store_short v[4:5], v0, off offset:3072
	v_cvt_pk_bf16_f32 v0, v53, s0
	global_store_short v[4:5], v0, off offset:3136
	v_cvt_pk_bf16_f32 v0, v21, s0
	global_store_short v[4:5], v0, off offset:3200
	v_cvt_pk_bf16_f32 v0, v69, s0
	s_mov_b32 s15, 0x9a02000
	global_store_short v[4:5], v0, off offset:3264
	v_add_co_u32_e32 v4, vcc, s15, v2
	v_cvt_pk_bf16_f32 v0, v38, s0
	s_nop 0
	v_addc_co_u32_e32 v5, vcc, 0, v3, vcc
	global_store_short v[4:5], v0, off
	v_cvt_pk_bf16_f32 v0, v54, s0
	global_store_short v[4:5], v0, off offset:64
	v_cvt_pk_bf16_f32 v0, v22, s0
	global_store_short v[4:5], v0, off offset:128
	v_cvt_pk_bf16_f32 v0, v70, s0
	global_store_short v[4:5], v0, off offset:192
	v_cvt_pk_bf16_f32 v0, v39, s0
	global_store_short v[4:5], v0, off offset:1024
	v_cvt_pk_bf16_f32 v0, v55, s0
	global_store_short v[4:5], v0, off offset:1088
	v_cvt_pk_bf16_f32 v0, v23, s0
	v_mul_f32_e32 v40, v40, v72
	global_store_short v[4:5], v0, off offset:1152
	v_cvt_pk_bf16_f32 v0, v71, s0
	v_mul_f32_e32 v56, v56, v72
	global_store_short v[4:5], v0, off offset:1216
	v_cvt_pk_bf16_f32 v0, v40, s0
	v_mul_f32_e32 v24, v24, v72
	global_store_short v[4:5], v0, off offset:2048
	v_cvt_pk_bf16_f32 v0, v56, s0
	v_mul_f32_e32 v8, v8, v72
	global_store_short v[4:5], v0, off offset:2112
	v_cvt_pk_bf16_f32 v0, v24, s0
	v_mul_f32_e32 v41, v41, v73
	global_store_short v[4:5], v0, off offset:2176
	v_cvt_pk_bf16_f32 v0, v8, s0
	v_mul_f32_e32 v57, v57, v73
	global_store_short v[4:5], v0, off offset:2240
	v_cvt_pk_bf16_f32 v0, v41, s0
	v_mul_f32_e32 v25, v25, v73
	global_store_short v[4:5], v0, off offset:3072
	v_cvt_pk_bf16_f32 v0, v57, s0
	v_mul_f32_e32 v9, v9, v73
	global_store_short v[4:5], v0, off offset:3136
	v_cvt_pk_bf16_f32 v0, v25, s0
	global_store_short v[4:5], v0, off offset:3200
	v_cvt_pk_bf16_f32 v0, v9, s0
	s_mov_b32 s15, 0x9a04000
	s_waitcnt lgkmcnt(1)
; DI bf16_t f2bf(float f) { return (bf16_t)(pk2(f, 0.f) & 0xffffu); }
; DI int crow(int r, int hi) { return (r & 3) + 8 * (r >> 2) + 4 * hi; }
; template <bool DIFF>
; DI void attn2_unit(int qb, const bf16_t* QO  , bf16_t* Ob, const bf16_t* K, const bf16_t* V  ,
;                    int ntile, float lam, const float* gain, float post, LAS unsigned char* lds) {
;     ...
;         for (int i = 0; i < 16; ++i) { bf16_t* rp = ob + (size_t)crow(i, hi) * 512;
;             rp[0] = f2bf(o1[0][i]); rp[32] = f2bf(o1[1][i]); rp[64] = f2bf(o1[2][i]); rp[96] = f2bf(o1[3][i]); }
; __global__ void __launch_bounds__(512, 2) fwd_megakernel(Params P) {
;     ...
;         for (int idx = c; idx < 512; idx += G) { const int qb = idx & 15, bh = idx >> 4, b = bh >> 2, hh = bh & 3;
	v_mul_f32_e32 v42, v42, v74
	global_store_short v[4:5], v0, off offset:3264
	v_add_co_u32_e32 v4, vcc, s15, v2
	v_mul_f32_e32 v58, v58, v74
	v_cvt_pk_bf16_f32 v0, v42, s0
	v_addc_co_u32_e32 v5, vcc, 0, v3, vcc
	v_mul_f32_e32 v26, v26, v74
	global_store_short v[4:5], v0, off
	v_cvt_pk_bf16_f32 v0, v58, s0
	v_mul_f32_e32 v10, v10, v74
	global_store_short v[4:5], v0, off offset:64
	v_cvt_pk_bf16_f32 v0, v26, s0
	v_mul_f32_e32 v43, v43, v75
	global_store_short v[4:5], v0, off offset:128
	v_cvt_pk_bf16_f32 v0, v10, s0
	v_mul_f32_e32 v59, v59, v75
	global_store_short v[4:5], v0, off offset:192
	v_cvt_pk_bf16_f32 v0, v43, s0
	v_mul_f32_e32 v27, v27, v75
	global_store_short v[4:5], v0, off offset:1024
	v_cvt_pk_bf16_f32 v0, v59, s0
	v_mul_f32_e32 v11, v11, v75
	global_store_short v[4:5], v0, off offset:1088
	v_cvt_pk_bf16_f32 v0, v27, s0
	v_mul_f32_e32 v44, v44, v76
	global_store_short v[4:5], v0, off offset:1152
	v_cvt_pk_bf16_f32 v0, v11, s0
	v_mul_f32_e32 v60, v60, v76
	global_store_short v[4:5], v0, off offset:1216
	v_cvt_pk_bf16_f32 v0, v44, s0
	v_mul_f32_e32 v28, v28, v76
	global_store_short v[4:5], v0, off offset:2048
	v_cvt_pk_bf16_f32 v0, v60, s0
	v_mul_f32_e32 v12, v12, v76
	global_store_short v[4:5], v0, off offset:2112
	v_cvt_pk_bf16_f32 v0, v28, s0
	v_mul_f32_e32 v45, v45, v77
	global_store_short v[4:5], v0, off offset:2176
	v_cvt_pk_bf16_f32 v0, v12, s0
	v_mul_f32_e32 v61, v61, v77
	global_store_short v[4:5], v0, off offset:2240
	v_cvt_pk_bf16_f32 v0, v45, s0
	v_mul_f32_e32 v29, v29, v77
	global_store_short v[4:5], v0, off offset:3072
	v_cvt_pk_bf16_f32 v0, v61, s0
	v_mul_f32_e32 v13, v13, v77
	global_store_short v[4:5], v0, off offset:3136
	v_cvt_pk_bf16_f32 v0, v29, s0
	s_mov_b32 s15, 0x9a06000
	s_waitcnt lgkmcnt(0)
	v_mul_f32_e32 v46, v46, v78
	global_store_short v[4:5], v0, off offset:3200
	v_cvt_pk_bf16_f32 v0, v13, s0
	v_add_co_u32_e32 v2, vcc, s15, v2
	v_mul_f32_e32 v62, v62, v78
	global_store_short v[4:5], v0, off offset:3264
	v_cvt_pk_bf16_f32 v0, v46, s0
	v_addc_co_u32_e32 v3, vcc, 0, v3, vcc
	v_mul_f32_e32 v30, v30, v78
	global_store_short v[2:3], v0, off
	v_cvt_pk_bf16_f32 v0, v62, s0
	v_mul_f32_e32 v14, v14, v78
	global_store_short v[2:3], v0, off offset:64
	v_cvt_pk_bf16_f32 v0, v30, s0
	v_mul_f32_e32 v47, v47, v79
	global_store_short v[2:3], v0, off offset:128
	v_cvt_pk_bf16_f32 v0, v14, s0
	v_mul_f32_e32 v63, v63, v79
	global_store_short v[2:3], v0, off offset:192
	v_cvt_pk_bf16_f32 v0, v47, s0
	v_mul_f32_e32 v31, v31, v79
	global_store_short v[2:3], v0, off offset:1024
	v_cvt_pk_bf16_f32 v0, v63, s0
	v_mul_f32_e32 v15, v15, v79
	global_store_short v[2:3], v0, off offset:1088
	v_cvt_pk_bf16_f32 v0, v31, s0
	v_mul_f32_e32 v48, v48, v80
	global_store_short v[2:3], v0, off offset:1152
	v_cvt_pk_bf16_f32 v0, v15, s0
	v_mul_f32_e32 v64, v64, v80
	global_store_short v[2:3], v0, off offset:1216
	v_cvt_pk_bf16_f32 v0, v48, s0
	v_mul_f32_e32 v32, v32, v80
	global_store_short v[2:3], v0, off offset:2048
	v_cvt_pk_bf16_f32 v0, v64, s0
	v_mul_f32_e32 v16, v16, v80
	global_store_short v[2:3], v0, off offset:2112
	v_cvt_pk_bf16_f32 v0, v32, s0
	v_mul_f32_e32 v49, v49, v81
	global_store_short v[2:3], v0, off offset:2176
	v_cvt_pk_bf16_f32 v0, v16, s0
	v_mul_f32_e32 v65, v65, v81
	global_store_short v[2:3], v0, off offset:2240
	v_cvt_pk_bf16_f32 v0, v49, s0
	v_mul_f32_e32 v33, v33, v81
	global_store_short v[2:3], v0, off offset:3072
	v_cvt_pk_bf16_f32 v0, v65, s0
	v_mul_f32_e32 v17, v17, v81
	global_store_short v[2:3], v0, off offset:3136
	v_cvt_pk_bf16_f32 v0, v33, s0
	s_add_i32 s14, s14, 16
	s_addk_i32 s13, 0x80
	global_store_short v[2:3], v0, off offset:3200
	v_cvt_pk_bf16_f32 v0, v17, s0
	s_bitcmp0_b32 s14, 4
	global_store_short v[2:3], v0, off offset:3264
	s_cbranch_scc1 .LBB0_1186
